# V-fragment prefetch lead 2, row-max tree spread over four PV gaps
# baseline (speedup 1.0000x reference)
.LBB5_822:
	s_lshl_b32 s24, s34, 1
	v_add_u32_e32 v183, s24, v212
	v_add_u32_e32 v215, s3, v208
	v_add_f32_e32 v251, v80, v81
	v_mfma_f32_32x32x16_bf16 v[112:127], v[172:175], v[236:239], v[220:235]
	s_add_i32 s24, s33, s64
	s_mov_b32 m0, s24
	v_lshl_add_u64 v[248:249], v[198:199], 0, s[36:37]
	global_load_lds_dwordx4 v[248:249], off
	v_add_f32_e32 v251, v82, v251
	v_add_f32_e32 v251, v83, v251
	v_add_f32_e32 v251, v84, v251
	v_add_f32_e32 v251, v85, v251
	v_cvt_pk_bf16_f32 v140, v80, v81
	v_cvt_pk_bf16_f32 v141, v82, v83
	ds_read_b128 v[172:175], v215
	v_mfma_f32_32x32x16_bf16 v[96:111], v[160:163], v[236:239], v[220:235]
	s_lshl_b32 s24, s3, 1
	s_add_i32 s24, s24, s66
	s_mov_b32 m0, s24
	v_lshl_add_u64 v[248:249], v[196:197], 0, s[36:37]
	global_load_lds_dwordx4 v[248:249], off
	v_add_f32_e32 v251, v86, v251
	v_add_f32_e32 v251, v87, v251
	v_add_f32_e32 v251, v88, v251
	v_add_f32_e32 v251, v89, v251
	v_cvt_pk_bf16_f32 v142, v84, v85
	v_cvt_pk_bf16_f32 v143, v86, v87
	ds_read_b128 v[160:163], v215 offset:512
	v_mfma_f32_32x32x16_bf16 v[112:127], v[168:171], v[240:243], v[112:127]
	s_addk_i32 s24, 0x2000
	s_mov_b32 m0, s24
	v_lshl_add_u64 v[248:249], v[194:195], 0, s[36:37]
	global_load_lds_dwordx4 v[248:249], off
	v_add_f32_e32 v251, v90, v251
	v_add_f32_e32 v251, v91, v251
	v_add_f32_e32 v251, v92, v251
	v_add_f32_e32 v251, v93, v251
	v_cvt_pk_bf16_f32 v136, v88, v89
	v_cvt_pk_bf16_f32 v137, v90, v91
	ds_read_b128 v[168:171], v215 offset:2048
	v_mfma_f32_32x32x16_bf16 v[96:111], v[152:155], v[240:243], v[96:111]
	v_add_f32_e32 v251, v94, v251
	v_add_f32_e32 v251, v95, v251
	v_add_f32_e32 v251, v64, v251
	v_add_f32_e32 v251, v65, v251
	v_cvt_pk_bf16_f32 v138, v92, v93
	v_cvt_pk_bf16_f32 v139, v94, v95
	ds_read_b128 v[152:155], v215 offset:2560
	v_mfma_f32_32x32x16_bf16 v[112:127], v[164:167], v[244:247], v[112:127]
	v_add_f32_e32 v251, v66, v251
	v_add_f32_e32 v251, v67, v251
	v_add_f32_e32 v251, v68, v251
	v_add_f32_e32 v251, v69, v251
	v_cvt_pk_bf16_f32 v132, v64, v65
	v_cvt_pk_bf16_f32 v133, v66, v67
	ds_read_b128 v[164:167], v215 offset:4096
	v_mfma_f32_32x32x16_bf16 v[96:111], v[148:151], v[244:247], v[96:111]
	v_add_f32_e32 v251, v70, v251
	v_add_f32_e32 v251, v71, v251
	v_add_f32_e32 v251, v72, v251
	v_add_f32_e32 v251, v73, v251
	v_cvt_pk_bf16_f32 v134, v68, v69
	v_cvt_pk_bf16_f32 v135, v70, v71
	ds_read_b128 v[148:151], v215 offset:4608
	v_mfma_f32_32x32x16_bf16 v[112:127], v[156:159], v[252:255], v[112:127]
	v_add_f32_e32 v251, v74, v251
	v_add_f32_e32 v251, v75, v251
	v_add_f32_e32 v251, v76, v251
	v_add_f32_e32 v251, v77, v251
	v_cvt_pk_bf16_f32 v128, v72, v73
	v_cvt_pk_bf16_f32 v129, v74, v75
	ds_read_b128 v[156:159], v215 offset:6144
	ds_read_b64_tr_b16 v[80:81], v183 offset:24576
	ds_read_b64_tr_b16 v[82:83], v183 offset:25088
	v_mfma_f32_32x32x16_bf16 v[96:111], v[144:147], v[252:255], v[96:111]
	v_add_f32_e32 v251, v78, v251
	v_add_f32_e32 v251, v79, v251
	v_cvt_pk_bf16_f32 v130, v76, v77
	v_cvt_pk_bf16_f32 v131, v78, v79
	ds_read_b128 v[144:147], v215 offset:6656
	ds_read_b64_tr_b16 v[84:85], v183 offset:28672
	ds_read_b64_tr_b16 v[86:87], v183 offset:29184
	s_waitcnt lgkmcnt(3)
	v_mfma_f32_32x32x16_bf16 v[16:31], v[140:143], v[80:83], v[16:31]
	ds_read_b64_tr_b16 v[88:89], v183 offset:32768
	ds_read_b64_tr_b16 v[90:91], v183 offset:33280
	v_max3_f32 v76, v112, v113, v114
	v_max3_f32 v76, v76, v115, v116
	v_max3_f32 v76, v76, v117, v118
	v_max3_f32 v76, v76, v119, v120
	v_max3_f32 v76, v76, v121, v122
	s_waitcnt lgkmcnt(2)
	v_mfma_f32_32x32x16_bf16 v[48:63], v[140:143], v[84:87], v[48:63]
	ds_read_b64_tr_b16 v[92:93], v183 offset:36864
	ds_read_b64_tr_b16 v[94:95], v183 offset:37376
	v_max3_f32 v76, v76, v123, v124
	v_max3_f32 v76, v76, v125, v126
	v_max3_f32 v76, v76, v127, v127
	v_max3_f32 v77, v96, v97, v98
	v_max3_f32 v77, v77, v99, v100
	s_waitcnt lgkmcnt(2)
	v_mfma_f32_32x32x16_bf16 v[32:47], v[140:143], v[88:91], v[32:47]
	ds_read_b64_tr_b16 v[64:65], v183 offset:25600
	ds_read_b64_tr_b16 v[66:67], v183 offset:26112
	v_max3_f32 v77, v77, v101, v102
	v_max3_f32 v77, v77, v103, v104
	v_max3_f32 v77, v77, v105, v106
	v_max3_f32 v77, v77, v107, v108
	s_waitcnt lgkmcnt(2)
	v_mfma_f32_32x32x16_bf16 v[0:15], v[140:143], v[92:95], v[0:15]
	ds_read_b64_tr_b16 v[68:69], v183 offset:29696
	ds_read_b64_tr_b16 v[70:71], v183 offset:30208
	v_max3_f32 v77, v77, v109, v110
	v_max3_f32 v77, v77, v111, v111
	v_max_f32_e32 v76, v76, v77
	v_mov_b32_e32 v77, v76
	s_waitcnt lgkmcnt(2)
	v_mfma_f32_32x32x16_bf16 v[16:31], v[136:139], v[64:67], v[16:31]
	ds_read_b64_tr_b16 v[80:81], v183 offset:33792
	ds_read_b64_tr_b16 v[82:83], v183 offset:34304
	v_permlane32_swap_b32_e32 v76, v77
	v_max_f32_e32 v77, v77, v77
	v_max_f32_e32 v76, v76, v76
	v_max_f32_e32 v76, v76, v77
	v_cmp_lt_f32_e32 vcc, s85, v76
	s_cmp_lg_u64 vcc, 0
	v_add_f32_e32 v214, v214, v251
	s_cselect_b64 s[46:47], -1, 0
	s_cbranch_vccnz .LBB5_830
.LBB5_823:
	s_waitcnt lgkmcnt(2)
	v_mfma_f32_32x32x16_bf16 v[48:63], v[136:139], v[68:71], v[48:63]
	ds_read_b64_tr_b16 v[84:85], v183 offset:37888
	ds_read_b64_tr_b16 v[86:87], v183 offset:38400
	v_exp_f32_e32 v112, v112
	v_exp_f32_e32 v113, v113
	v_exp_f32_e32 v114, v114
	s_waitcnt lgkmcnt(2)
	v_mfma_f32_32x32x16_bf16 v[32:47], v[136:139], v[80:83], v[32:47]
	ds_read_b64_tr_b16 v[88:89], v183 offset:26624
	ds_read_b64_tr_b16 v[90:91], v183 offset:27136
	v_exp_f32_e32 v115, v115
	v_exp_f32_e32 v116, v116
	v_exp_f32_e32 v117, v117
	s_waitcnt lgkmcnt(2)
	v_mfma_f32_32x32x16_bf16 v[0:15], v[136:139], v[84:87], v[0:15]
	ds_read_b64_tr_b16 v[92:93], v183 offset:30720
	ds_read_b64_tr_b16 v[94:95], v183 offset:31232
	v_exp_f32_e32 v118, v118
	v_exp_f32_e32 v119, v119
	v_exp_f32_e32 v120, v120
	s_waitcnt lgkmcnt(2)
	v_mfma_f32_32x32x16_bf16 v[16:31], v[132:135], v[88:91], v[16:31]
	ds_read_b64_tr_b16 v[64:65], v183 offset:34816
	ds_read_b64_tr_b16 v[66:67], v183 offset:35328
	v_exp_f32_e32 v121, v121
	v_exp_f32_e32 v122, v122
	v_exp_f32_e32 v123, v123
	s_waitcnt lgkmcnt(2)
	v_mfma_f32_32x32x16_bf16 v[48:63], v[132:135], v[92:95], v[48:63]
	ds_read_b64_tr_b16 v[68:69], v183 offset:38912
	ds_read_b64_tr_b16 v[70:71], v183 offset:39424
	v_exp_f32_e32 v124, v124
	v_exp_f32_e32 v125, v125
	v_exp_f32_e32 v126, v126
	s_waitcnt lgkmcnt(2)
	v_mfma_f32_32x32x16_bf16 v[32:47], v[132:135], v[64:67], v[32:47]
	ds_read_b64_tr_b16 v[80:81], v183 offset:27648
	ds_read_b64_tr_b16 v[82:83], v183 offset:28160
	v_exp_f32_e32 v127, v127
	v_exp_f32_e32 v96, v96
	v_exp_f32_e32 v97, v97
	s_waitcnt lgkmcnt(2)
	v_mfma_f32_32x32x16_bf16 v[0:15], v[132:135], v[68:71], v[0:15]
	ds_read_b64_tr_b16 v[84:85], v183 offset:31744
	ds_read_b64_tr_b16 v[86:87], v183 offset:32256
	v_exp_f32_e32 v98, v98
	v_exp_f32_e32 v99, v99
	v_exp_f32_e32 v100, v100
	s_waitcnt lgkmcnt(2)
	v_mfma_f32_32x32x16_bf16 v[16:31], v[128:131], v[80:83], v[16:31]
	ds_read_b64_tr_b16 v[88:89], v183 offset:35840
	ds_read_b64_tr_b16 v[90:91], v183 offset:36352
	v_exp_f32_e32 v101, v101
	v_exp_f32_e32 v102, v102
	v_exp_f32_e32 v103, v103
	s_waitcnt lgkmcnt(2)
	v_mfma_f32_32x32x16_bf16 v[48:63], v[128:131], v[84:87], v[48:63]
	ds_read_b64_tr_b16 v[92:93], v183 offset:39936
	ds_read_b64_tr_b16 v[94:95], v183 offset:40448
	v_exp_f32_e32 v104, v104
	v_exp_f32_e32 v105, v105
	v_exp_f32_e32 v106, v106
	s_waitcnt lgkmcnt(2)
	v_mfma_f32_32x32x16_bf16 v[32:47], v[128:131], v[88:91], v[32:47]
	v_exp_f32_e32 v107, v107
	v_exp_f32_e32 v108, v108
	v_exp_f32_e32 v109, v109
	s_waitcnt lgkmcnt(0)
	v_mfma_f32_32x32x16_bf16 v[0:15], v[128:131], v[92:95], v[0:15]
	v_exp_f32_e32 v110, v110
	v_exp_f32_e32 v111, v111
	s_waitcnt vmcnt(3) lgkmcnt(0)
	s_barrier
	s_andn2_b64 vcc, exec, s[46:47]
	v_add_u32_e32 v183, s80, v184
	s_cbranch_vccnz .LBB5_825
	s_waitcnt lgkmcnt(0)
	ds_read_b128 v[72:75], v183 offset:96
	ds_read_b128 v[76:79], v183 offset:64
	ds_read_b128 v[80:83], v183 offset:32
	ds_read_b128 v[84:87], v183
	s_waitcnt lgkmcnt(3)
	v_pk_mul_f32 v[28:29], v[28:29], v[72:73]
	s_waitcnt lgkmcnt(2)
	v_pk_mul_f32 v[24:25], v[24:25], v[76:77]
	s_waitcnt lgkmcnt(1)
	v_pk_mul_f32 v[20:21], v[20:21], v[80:81]
	v_pk_mul_f32 v[30:31], v[30:31], v[74:75]
	v_pk_mul_f32 v[26:27], v[26:27], v[78:79]
	v_pk_mul_f32 v[22:23], v[22:23], v[82:83]
	s_waitcnt lgkmcnt(0)
	v_pk_mul_f32 v[18:19], v[18:19], v[86:87]
	v_pk_mul_f32 v[16:17], v[16:17], v[84:85]
	v_pk_mul_f32 v[60:61], v[60:61], v[72:73]
	v_pk_mul_f32 v[56:57], v[56:57], v[76:77]
	v_pk_mul_f32 v[52:53], v[52:53], v[80:81]
	v_pk_mul_f32 v[62:63], v[62:63], v[74:75]
	v_pk_mul_f32 v[58:59], v[58:59], v[78:79]
	v_pk_mul_f32 v[54:55], v[54:55], v[82:83]
	v_pk_mul_f32 v[50:51], v[50:51], v[86:87]
	v_pk_mul_f32 v[48:49], v[48:49], v[84:85]
	v_pk_mul_f32 v[44:45], v[44:45], v[72:73]
	v_pk_mul_f32 v[40:41], v[40:41], v[76:77]
	v_pk_mul_f32 v[36:37], v[36:37], v[80:81]
	v_pk_mul_f32 v[46:47], v[46:47], v[74:75]
	v_pk_mul_f32 v[42:43], v[42:43], v[78:79]
	v_pk_mul_f32 v[38:39], v[38:39], v[82:83]
	v_pk_mul_f32 v[34:35], v[34:35], v[86:87]
	v_pk_mul_f32 v[32:33], v[32:33], v[84:85]
	v_pk_mul_f32 v[12:13], v[12:13], v[72:73]
	v_pk_mul_f32 v[8:9], v[8:9], v[76:77]
	v_pk_mul_f32 v[4:5], v[4:5], v[80:81]
	v_pk_mul_f32 v[14:15], v[14:15], v[74:75]
	v_pk_mul_f32 v[10:11], v[10:11], v[78:79]
	v_pk_mul_f32 v[6:7], v[6:7], v[82:83]
	v_pk_mul_f32 v[2:3], v[2:3], v[86:87]
	v_pk_mul_f32 v[0:1], v[0:1], v[84:85]
.LBB5_825:
	s_add_i32 s24, s3, 0x2000
	s_cmpk_lg_i32 s3, 0x4000
	s_cselect_b32 s25, s24, 0
	s_lshl_b32 s24, s33, 1
	v_add_u32_e32 v213, s24, v212
	v_add_u32_e32 v215, s25, v208
	v_add_f32_e32 v251, v112, v113
	v_mfma_f32_32x32x16_bf16 v[80:95], v[172:175], v[236:239], v[220:235]
	s_add_i32 s24, s3, s64
	s_mov_b32 m0, s24
	v_add_f32_e32 v251, v114, v251
	global_load_lds_dwordx4 v[198:199], off
	v_add_f32_e32 v251, v115, v251
	v_add_f32_e32 v251, v116, v251
	v_add_f32_e32 v251, v117, v251
	v_cvt_pk_bf16_f32 v140, v112, v113
	v_cvt_pk_bf16_f32 v141, v114, v115
	ds_read_b128 v[172:175], v215
	v_mfma_f32_32x32x16_bf16 v[64:79], v[160:163], v[236:239], v[220:235]
	s_lshl_b32 s24, s25, 1
	s_add_i32 s24, s24, s66
	s_mov_b32 m0, s24
	v_add_f32_e32 v251, v118, v251
	global_load_lds_dwordx4 v[196:197], off
	v_add_f32_e32 v251, v119, v251
	v_add_f32_e32 v251, v120, v251
	v_add_f32_e32 v251, v121, v251
	v_cvt_pk_bf16_f32 v142, v116, v117
	v_cvt_pk_bf16_f32 v143, v118, v119
	ds_read_b128 v[160:163], v215 offset:512
	v_mfma_f32_32x32x16_bf16 v[80:95], v[168:171], v[240:243], v[80:95]
	s_addk_i32 s24, 0x2000
	s_mov_b32 m0, s24
	v_add_f32_e32 v251, v122, v251
	global_load_lds_dwordx4 v[194:195], off
	v_add_f32_e32 v251, v123, v251
	v_add_f32_e32 v251, v124, v251
	v_add_f32_e32 v251, v125, v251
	v_cvt_pk_bf16_f32 v136, v120, v121
	v_cvt_pk_bf16_f32 v137, v122, v123
	ds_read_b128 v[168:171], v215 offset:2048
	v_mfma_f32_32x32x16_bf16 v[64:79], v[152:155], v[240:243], v[64:79]
	v_add_f32_e32 v251, v126, v251
	v_add_f32_e32 v251, v127, v251
	v_add_f32_e32 v251, v96, v251
	v_add_f32_e32 v251, v97, v251
	v_cvt_pk_bf16_f32 v138, v124, v125
	v_cvt_pk_bf16_f32 v139, v126, v127
	ds_read_b128 v[152:155], v215 offset:2560
	v_mfma_f32_32x32x16_bf16 v[80:95], v[164:167], v[244:247], v[80:95]
	v_add_f32_e32 v251, v98, v251
	v_add_f32_e32 v251, v99, v251
	v_add_f32_e32 v251, v100, v251
	v_add_f32_e32 v251, v101, v251
	v_cvt_pk_bf16_f32 v132, v96, v97
	v_cvt_pk_bf16_f32 v133, v98, v99
	ds_read_b128 v[164:167], v215 offset:4096
	v_mfma_f32_32x32x16_bf16 v[64:79], v[148:151], v[244:247], v[64:79]
	v_add_f32_e32 v251, v102, v251
	v_add_f32_e32 v251, v103, v251
	v_add_f32_e32 v251, v104, v251
	v_add_f32_e32 v251, v105, v251
	v_cvt_pk_bf16_f32 v134, v100, v101
	v_cvt_pk_bf16_f32 v135, v102, v103
	ds_read_b128 v[148:151], v215 offset:4608
	v_mfma_f32_32x32x16_bf16 v[80:95], v[156:159], v[252:255], v[80:95]
	v_add_f32_e32 v251, v106, v251
	v_add_f32_e32 v251, v107, v251
	v_add_f32_e32 v251, v108, v251
	v_add_f32_e32 v251, v109, v251
	v_cvt_pk_bf16_f32 v128, v104, v105
	v_cvt_pk_bf16_f32 v129, v106, v107
	ds_read_b128 v[156:159], v215 offset:6144
	ds_read_b64_tr_b16 v[112:113], v213 offset:24576
	ds_read_b64_tr_b16 v[114:115], v213 offset:25088
	v_mfma_f32_32x32x16_bf16 v[64:79], v[144:147], v[252:255], v[64:79]
	v_add_f32_e32 v251, v110, v251
	v_add_f32_e32 v251, v111, v251
	v_cvt_pk_bf16_f32 v130, v108, v109
	v_cvt_pk_bf16_f32 v131, v110, v111
	ds_read_b128 v[144:147], v215 offset:6656
	ds_read_b64_tr_b16 v[116:117], v213 offset:28672
	ds_read_b64_tr_b16 v[118:119], v213 offset:29184
	s_waitcnt lgkmcnt(3)
	v_mfma_f32_32x32x16_bf16 v[16:31], v[140:143], v[112:115], v[16:31]
	ds_read_b64_tr_b16 v[120:121], v213 offset:32768
	ds_read_b64_tr_b16 v[122:123], v213 offset:33280
	v_max3_f32 v108, v80, v81, v82
	v_max3_f32 v108, v108, v83, v84
	v_max3_f32 v108, v108, v85, v86
	v_max3_f32 v108, v108, v87, v88
	v_max3_f32 v108, v108, v89, v90
	s_waitcnt lgkmcnt(2)
	v_mfma_f32_32x32x16_bf16 v[48:63], v[140:143], v[116:119], v[48:63]
	ds_read_b64_tr_b16 v[124:125], v213 offset:36864
	ds_read_b64_tr_b16 v[126:127], v213 offset:37376
	v_max3_f32 v108, v108, v91, v92
	v_max3_f32 v108, v108, v93, v94
	v_max3_f32 v108, v108, v95, v95
	v_max3_f32 v109, v64, v65, v66
	v_max3_f32 v109, v109, v67, v68
	s_waitcnt lgkmcnt(2)
	v_mfma_f32_32x32x16_bf16 v[32:47], v[140:143], v[120:123], v[32:47]
	ds_read_b64_tr_b16 v[96:97], v213 offset:25600
	ds_read_b64_tr_b16 v[98:99], v213 offset:26112
	v_max3_f32 v109, v109, v69, v70
	v_max3_f32 v109, v109, v71, v72
	v_max3_f32 v109, v109, v73, v74
	v_max3_f32 v109, v109, v75, v76
	s_waitcnt lgkmcnt(2)
	v_mfma_f32_32x32x16_bf16 v[0:15], v[140:143], v[124:127], v[0:15]
	ds_read_b64_tr_b16 v[100:101], v213 offset:29696
	ds_read_b64_tr_b16 v[102:103], v213 offset:30208
	v_max3_f32 v109, v109, v77, v78
	v_max3_f32 v109, v109, v79, v79
	v_max_f32_e32 v108, v108, v109
	v_mov_b32_e32 v109, v108
	s_waitcnt lgkmcnt(2)
	v_mfma_f32_32x32x16_bf16 v[16:31], v[136:139], v[96:99], v[16:31]
	ds_read_b64_tr_b16 v[112:113], v213 offset:33792
	ds_read_b64_tr_b16 v[114:115], v213 offset:34304
	v_permlane32_swap_b32_e32 v108, v109
	v_max_f32_e32 v109, v109, v109
	v_max_f32_e32 v108, v108, v108
	v_max_f32_e32 v108, v108, v109
	v_cmp_lt_f32_e32 vcc, s85, v108
	s_cmp_lg_u64 vcc, 0
	v_add_f32_e32 v214, v214, v251
	s_cselect_b64 s[46:47], -1, 0
	s_cbranch_vccnz .LBB5_833
.LBB5_826:
	s_waitcnt lgkmcnt(2)
	v_mfma_f32_32x32x16_bf16 v[48:63], v[136:139], v[100:103], v[48:63]
	ds_read_b64_tr_b16 v[116:117], v213 offset:37888
	ds_read_b64_tr_b16 v[118:119], v213 offset:38400
	v_exp_f32_e32 v80, v80
	v_exp_f32_e32 v81, v81
	v_exp_f32_e32 v82, v82
	s_waitcnt lgkmcnt(2)
	v_mfma_f32_32x32x16_bf16 v[32:47], v[136:139], v[112:115], v[32:47]
	ds_read_b64_tr_b16 v[120:121], v213 offset:26624
	ds_read_b64_tr_b16 v[122:123], v213 offset:27136
	v_exp_f32_e32 v83, v83
	v_exp_f32_e32 v84, v84
	v_exp_f32_e32 v85, v85
	s_waitcnt lgkmcnt(2)
	v_mfma_f32_32x32x16_bf16 v[0:15], v[136:139], v[116:119], v[0:15]
	ds_read_b64_tr_b16 v[124:125], v213 offset:30720
	ds_read_b64_tr_b16 v[126:127], v213 offset:31232
	v_exp_f32_e32 v86, v86
	v_exp_f32_e32 v87, v87
	v_exp_f32_e32 v88, v88
	s_waitcnt lgkmcnt(2)
	v_mfma_f32_32x32x16_bf16 v[16:31], v[132:135], v[120:123], v[16:31]
	ds_read_b64_tr_b16 v[96:97], v213 offset:34816
	ds_read_b64_tr_b16 v[98:99], v213 offset:35328
	v_exp_f32_e32 v89, v89
	v_exp_f32_e32 v90, v90
	v_exp_f32_e32 v91, v91
	s_waitcnt lgkmcnt(2)
	v_mfma_f32_32x32x16_bf16 v[48:63], v[132:135], v[124:127], v[48:63]
	ds_read_b64_tr_b16 v[100:101], v213 offset:38912
	ds_read_b64_tr_b16 v[102:103], v213 offset:39424
	v_exp_f32_e32 v92, v92
	v_exp_f32_e32 v93, v93
	v_exp_f32_e32 v94, v94
	s_waitcnt lgkmcnt(2)
	v_mfma_f32_32x32x16_bf16 v[32:47], v[132:135], v[96:99], v[32:47]
	ds_read_b64_tr_b16 v[112:113], v213 offset:27648
	ds_read_b64_tr_b16 v[114:115], v213 offset:28160
	v_exp_f32_e32 v95, v95
	v_exp_f32_e32 v64, v64
	v_exp_f32_e32 v65, v65
	s_waitcnt lgkmcnt(2)
	v_mfma_f32_32x32x16_bf16 v[0:15], v[132:135], v[100:103], v[0:15]
	ds_read_b64_tr_b16 v[116:117], v213 offset:31744
	ds_read_b64_tr_b16 v[118:119], v213 offset:32256
	v_exp_f32_e32 v66, v66
	v_exp_f32_e32 v67, v67
	v_exp_f32_e32 v68, v68
	s_waitcnt lgkmcnt(2)
	v_mfma_f32_32x32x16_bf16 v[16:31], v[128:131], v[112:115], v[16:31]
	ds_read_b64_tr_b16 v[120:121], v213 offset:35840
	ds_read_b64_tr_b16 v[122:123], v213 offset:36352
	v_exp_f32_e32 v69, v69
	v_exp_f32_e32 v70, v70
	v_exp_f32_e32 v71, v71
	s_waitcnt lgkmcnt(2)
	v_mfma_f32_32x32x16_bf16 v[48:63], v[128:131], v[116:119], v[48:63]
	ds_read_b64_tr_b16 v[124:125], v213 offset:39936
	ds_read_b64_tr_b16 v[126:127], v213 offset:40448
	v_exp_f32_e32 v72, v72
	v_exp_f32_e32 v73, v73
	v_exp_f32_e32 v74, v74
	s_waitcnt lgkmcnt(2)
	v_mfma_f32_32x32x16_bf16 v[32:47], v[128:131], v[120:123], v[32:47]
	v_exp_f32_e32 v75, v75
	v_exp_f32_e32 v76, v76
	v_exp_f32_e32 v77, v77
	s_waitcnt lgkmcnt(0)
	v_mfma_f32_32x32x16_bf16 v[0:15], v[128:131], v[124:127], v[0:15]
	v_exp_f32_e32 v78, v78
	v_exp_f32_e32 v79, v79
	s_waitcnt vmcnt(3) lgkmcnt(0)
	s_barrier
	s_andn2_b64 vcc, exec, s[46:47]
	s_cbranch_vccnz .LBB5_828
	s_waitcnt lgkmcnt(0)
	ds_read_b128 v[96:99], v183 offset:96
	ds_read_b128 v[100:103], v183 offset:64
	ds_read_b128 v[104:107], v183 offset:32
	ds_read_b128 v[108:111], v183
	s_waitcnt lgkmcnt(3)
	v_pk_mul_f32 v[28:29], v[28:29], v[96:97]
	s_waitcnt lgkmcnt(2)
	v_pk_mul_f32 v[24:25], v[24:25], v[100:101]
	s_waitcnt lgkmcnt(1)
	v_pk_mul_f32 v[20:21], v[20:21], v[104:105]
	v_pk_mul_f32 v[30:31], v[30:31], v[98:99]
	v_pk_mul_f32 v[26:27], v[26:27], v[102:103]
	v_pk_mul_f32 v[22:23], v[22:23], v[106:107]
	s_waitcnt lgkmcnt(0)
	v_pk_mul_f32 v[18:19], v[18:19], v[110:111]
	v_pk_mul_f32 v[16:17], v[16:17], v[108:109]
	v_pk_mul_f32 v[60:61], v[60:61], v[96:97]
	v_pk_mul_f32 v[56:57], v[56:57], v[100:101]
	v_pk_mul_f32 v[52:53], v[52:53], v[104:105]
	v_pk_mul_f32 v[62:63], v[62:63], v[98:99]
	v_pk_mul_f32 v[58:59], v[58:59], v[102:103]
	v_pk_mul_f32 v[54:55], v[54:55], v[106:107]
	v_pk_mul_f32 v[50:51], v[50:51], v[110:111]
	v_pk_mul_f32 v[48:49], v[48:49], v[108:109]
	v_pk_mul_f32 v[44:45], v[44:45], v[96:97]
	v_pk_mul_f32 v[40:41], v[40:41], v[100:101]
	v_pk_mul_f32 v[36:37], v[36:37], v[104:105]
	v_pk_mul_f32 v[46:47], v[46:47], v[98:99]
	v_pk_mul_f32 v[42:43], v[42:43], v[102:103]
	v_pk_mul_f32 v[38:39], v[38:39], v[106:107]
	v_pk_mul_f32 v[34:35], v[34:35], v[110:111]
	v_pk_mul_f32 v[32:33], v[32:33], v[108:109]
	v_pk_mul_f32 v[12:13], v[12:13], v[96:97]
	v_pk_mul_f32 v[8:9], v[8:9], v[100:101]
	v_pk_mul_f32 v[4:5], v[4:5], v[104:105]
	v_pk_mul_f32 v[14:15], v[14:15], v[98:99]
	v_pk_mul_f32 v[10:11], v[10:11], v[102:103]
	v_pk_mul_f32 v[6:7], v[6:7], v[106:107]
	v_pk_mul_f32 v[2:3], v[2:3], v[110:111]
	v_pk_mul_f32 v[0:1], v[0:1], v[108:109]
